# conversion-loop bf16 weight stores write-back (plain) instead of write-through sc1
# speedup vs baseline: 1.0100x; 1.0100x over previous
; #define LAS __attribute__((address_space(3)))
; __device__ __forceinline__ void tr_item_cu(const float* __restrict__ W, int K, int N, bf16* __restrict__ WT, const float* rowgain, int mode, LAS unsigned char* buf, int item, int wave, int lane) {
;     ...
;     for (int m = 0; m < 8; ++m) { const int row = 16 * wave + 2 * m + hr;
;         const u32x4 o = *(const LAS u32x4*)(buf + row * TCP + c * 16);
;         asm volatile("global_store_dwordx4 %0, %1, off sc1\n\ts_nop 1" :: "v"(WT + (size_t)row_map(mode, n0 + row) * K + k0 + 8 * c), "v"(o) : "memory"); }
; __global__ void __launch_bounds__(NTHREADS, 2) mega_fwd(Args args) {
;     ...
;         for (int it = bid; it < DEPTH * I_LAYER; it += G, nbuf ^= 1) {
;             const int itr = DEPTH * I_LAYER - 1 - it;
;             const int l = itr / I_LAYER; int r = itr - l * I_LAYER;
;             unsigned char* WL = P_WL(l);
;             const float* W; int K, N, mode = 0; bf16* WT; const float* rg = nullptr;
;             if (r < 3 * I_GU) { const int w = r / I_GU; r -= w * I_GU;
;                 if (w < 2) { W = args.in[2 + w] + (size_t)l * D * FF; K = D; N = FF; WT = (bf16*)(WL + OFF_WGU1); rg = args.in[1] + (size_t)l * D; mode = 1 + w; }
;                 else { W = args.in[4] + (size_t)l * FF * D; K = FF; N = D; WT = (bf16*)(WL + OFF_WD1); } }
;             else if ((r -= 3 * I_GU) < 3 * I_GU) { const int w = r / I_GU; r -= w * I_GU;
;                 if (w < 2) { W = args.in[13 + w] + (size_t)l * D * FF; K = D; N = FF; WT = (bf16*)(WL + OFF_WGU2); rg = args.in[12] + (size_t)l * D; mode = 1 + w; }
;                 else { W = args.in[15] + (size_t)l * FF * D; K = FF; N = D; WT = (bf16*)(WL + OFF_WD2); } }
;             else if ((r -= 3 * I_GU) < I_IN) { W = args.in[6] + (size_t)l * D * INW; K = D; N = INW; WT = (bf16*)(WL + OFF_WIN); rg = args.in[5] + (size_t)l * D; mode = 3; }
;             else { r -= I_IN; W = args.in[11] + (size_t)l * D * D; K = D; N = D; WT = (bf16*)(WL + OFF_WOUT); }
;             tr_item_cu(W, K, N, WT, rg, mode, lds + nbuf * TC_BUF, r, wave, lane);
;         }
.LBB0_32:
	v_ashrrev_i32_e32 v8, 31, v9
	v_mul_lo_u32 v10, s21, v9
	v_mul_lo_u32 v11, s20, v8
	v_mad_u64_u32 v[8:9], s[20:21], s20, v9, 0
	s_load_dwordx4 s[20:23], s[0:1], 0x88
	v_add3_u32 v9, v9, v11, v10
	v_lshl_add_u64 v[6:7], v[8:9], 1, v[6:7]
	s_waitcnt lgkmcnt(0)
	global_store_dwordx4 v[6:7], v[48:51], off
	s_nop 1
	s_xor_b32 s43, s43, 1
	s_add_i32 s44, s44, s100
	s_sub_i32 s38, s38, s100
	s_sub_i32 s39, s39, s100
	s_mov_b32 s100, s99
	s_cmp_gt_i32 s44, s101
	s_cbranch_scc1 .LBB0_184

; #define LAS __attribute__((address_space(3)))
; __device__ __forceinline__ int row_map(int mode, int n) {
;     if (mode == 0) return n;
;     if (mode == 1) return (n >> 7) * 256 + (n & 127);
;     if (mode == 2) return (n >> 7) * 256 + 128 + (n & 127);
;     if (n < 1024 || n >= 3072) { const int c = n & 31; return (n & ~31) + 16 * ((c >> 2) & 1) + 4 * (c >> 3) + (c & 3); }
;     const int dd = (n - 1024) & 127; return (n - dd) + ((((dd >> 4) & 3) << 5) | ((dd >> 6) << 4) | (dd & 15));
; __device__ __forceinline__ void tr_item_cu(const float* __restrict__ W, int K, int N, bf16* __restrict__ WT, const float* rowgain, int mode, LAS unsigned char* buf, int item, int wave, int lane) {
;     ...
;     for (int m = 0; m < 8; ++m) { const int row = 16 * wave + 2 * m + hr;
;         const u32x4 o = *(const LAS u32x4*)(buf + row * TCP + c * 16);
;         asm volatile("global_store_dwordx4 %0, %1, off sc1\n\ts_nop 1" :: "v"(WT + (size_t)row_map(mode, n0 + row) * K + k0 + 8 * c), "v"(o) : "memory"); }
.LBB0_73:
	s_lshl_b64 s[26:27], s[26:27], 1
	s_add_u32 s24, s24, s26
	s_addc_u32 s25, s25, s27
	v_ashrrev_i32_e32 v10, 31, v9
	v_lshl_add_u64 v[6:7], s[24:25], 0, v[68:69]
	v_mul_lo_u32 v12, s21, v9
	v_mul_lo_u32 v13, s20, v10
	v_mad_u64_u32 v[10:11], s[24:25], s20, v9, 0
	v_add3_u32 v11, v11, v13, v12
	v_lshl_add_u64 v[10:11], v[10:11], 1, v[6:7]
	s_waitcnt lgkmcnt(0)
	global_store_dwordx4 v[10:11], v[20:23], off
	s_nop 1
	s_cmp_lt_i32 s45, 1
	v_add_u32_e32 v9, s22, v82
	s_cbranch_scc1 .LBB0_78
	s_cmp_gt_i32 s45, 1
	s_cbranch_scc0 .LBB0_79
	s_cmp_eq_u32 s45, 2
	s_mov_b64 s[24:25], -1
	s_cbranch_scc0 .LBB0_77
	v_lshlrev_b32_e32 v10, 1, v9
	v_and_or_b32 v10, v10, s40, v110
	s_mov_b64 s[24:25], 0

; #define LAS __attribute__((address_space(3)))
; __device__ __forceinline__ int row_map(int mode, int n) {
;     if (mode == 0) return n;
;     if (mode == 1) return (n >> 7) * 256 + (n & 127);
;     if (mode == 2) return (n >> 7) * 256 + 128 + (n & 127);
;     if (n < 1024 || n >= 3072) { const int c = n & 31; return (n & ~31) + 16 * ((c >> 2) & 1) + 4 * (c >> 3) + (c & 3); }
;     const int dd = (n - 1024) & 127; return (n - dd) + ((((dd >> 4) & 3) << 5) | ((dd >> 6) << 4) | (dd & 15));
; __device__ __forceinline__ void tr_item_cu(const float* __restrict__ W, int K, int N, bf16* __restrict__ WT, const float* rowgain, int mode, LAS unsigned char* buf, int item, int wave, int lane) {
;     ...
;     for (int m = 0; m < 8; ++m) { const int row = 16 * wave + 2 * m + hr;
;         const u32x4 o = *(const LAS u32x4*)(buf + row * TCP + c * 16);
;         asm volatile("global_store_dwordx4 %0, %1, off sc1\n\ts_nop 1" :: "v"(WT + (size_t)row_map(mode, n0 + row) * K + k0 + 8 * c), "v"(o) : "memory"); }
.LBB0_89:
	v_ashrrev_i32_e32 v9, 31, v10
	v_mul_lo_u32 v12, s21, v10
	v_mul_lo_u32 v9, s20, v9
	v_mad_u64_u32 v[10:11], s[24:25], s20, v10, 0
	v_add3_u32 v11, v11, v9, v12
	v_lshl_add_u64 v[10:11], v[10:11], 1, v[6:7]
	s_waitcnt lgkmcnt(0)
	global_store_dwordx4 v[10:11], v[24:27], off
	s_nop 1
	s_cmp_lt_i32 s45, 1
	v_add_u32_e32 v9, s22, v86
	s_cbranch_scc1 .LBB0_94
	s_cmp_gt_i32 s45, 1
	s_cbranch_scc0 .LBB0_95
	s_cmp_eq_u32 s45, 2
	s_mov_b64 s[24:25], -1
	s_cbranch_scc0 .LBB0_93
	v_lshlrev_b32_e32 v10, 1, v9
	v_and_or_b32 v10, v10, s40, v111
	s_mov_b64 s[24:25], 0

; #define LAS __attribute__((address_space(3)))
; __device__ __forceinline__ int row_map(int mode, int n) {
;     if (mode == 0) return n;
;     if (mode == 1) return (n >> 7) * 256 + (n & 127);
;     if (mode == 2) return (n >> 7) * 256 + 128 + (n & 127);
;     if (n < 1024 || n >= 3072) { const int c = n & 31; return (n & ~31) + 16 * ((c >> 2) & 1) + 4 * (c >> 3) + (c & 3); }
;     const int dd = (n - 1024) & 127; return (n - dd) + ((((dd >> 4) & 3) << 5) | ((dd >> 6) << 4) | (dd & 15));
; __device__ __forceinline__ void tr_item_cu(const float* __restrict__ W, int K, int N, bf16* __restrict__ WT, const float* rowgain, int mode, LAS unsigned char* buf, int item, int wave, int lane) {
;     ...
;     for (int m = 0; m < 8; ++m) { const int row = 16 * wave + 2 * m + hr;
;         const u32x4 o = *(const LAS u32x4*)(buf + row * TCP + c * 16);
;         asm volatile("global_store_dwordx4 %0, %1, off sc1\n\ts_nop 1" :: "v"(WT + (size_t)row_map(mode, n0 + row) * K + k0 + 8 * c), "v"(o) : "memory"); }
.LBB0_105:
	v_ashrrev_i32_e32 v9, 31, v10
	v_mul_lo_u32 v12, s21, v10
	v_mul_lo_u32 v9, s20, v9
	v_mad_u64_u32 v[10:11], s[24:25], s20, v10, 0
	v_add3_u32 v11, v11, v9, v12
	v_lshl_add_u64 v[10:11], v[10:11], 1, v[6:7]
	s_waitcnt lgkmcnt(0)
	global_store_dwordx4 v[10:11], v[28:31], off
	s_nop 1
	s_cmp_lt_i32 s45, 1
	v_add_u32_e32 v9, s22, v90
	s_cbranch_scc1 .LBB0_110
	s_cmp_gt_i32 s45, 1
	s_cbranch_scc0 .LBB0_111
	s_cmp_eq_u32 s45, 2
	s_mov_b64 s[24:25], -1
	s_cbranch_scc0 .LBB0_109
	v_lshlrev_b32_e32 v10, 1, v9
	v_and_or_b32 v10, v10, s40, v112
	s_mov_b64 s[24:25], 0

; #define LAS __attribute__((address_space(3)))
; __device__ __forceinline__ int row_map(int mode, int n) {
;     if (mode == 0) return n;
;     if (mode == 1) return (n >> 7) * 256 + (n & 127);
;     if (mode == 2) return (n >> 7) * 256 + 128 + (n & 127);
;     if (n < 1024 || n >= 3072) { const int c = n & 31; return (n & ~31) + 16 * ((c >> 2) & 1) + 4 * (c >> 3) + (c & 3); }
;     const int dd = (n - 1024) & 127; return (n - dd) + ((((dd >> 4) & 3) << 5) | ((dd >> 6) << 4) | (dd & 15));
; __device__ __forceinline__ void tr_item_cu(const float* __restrict__ W, int K, int N, bf16* __restrict__ WT, const float* rowgain, int mode, LAS unsigned char* buf, int item, int wave, int lane) {
;     ...
;     for (int m = 0; m < 8; ++m) { const int row = 16 * wave + 2 * m + hr;
;         const u32x4 o = *(const LAS u32x4*)(buf + row * TCP + c * 16);
;         asm volatile("global_store_dwordx4 %0, %1, off sc1\n\ts_nop 1" :: "v"(WT + (size_t)row_map(mode, n0 + row) * K + k0 + 8 * c), "v"(o) : "memory"); }
.LBB0_121:
	v_ashrrev_i32_e32 v9, 31, v10
	v_mul_lo_u32 v12, s21, v10
	v_mul_lo_u32 v9, s20, v9
	v_mad_u64_u32 v[10:11], s[24:25], s20, v10, 0
	v_add3_u32 v11, v11, v9, v12
	v_lshl_add_u64 v[10:11], v[10:11], 1, v[6:7]
	s_waitcnt lgkmcnt(0)
	global_store_dwordx4 v[10:11], v[32:35], off
	s_nop 1
	s_cmp_lt_i32 s45, 1
	v_add_u32_e32 v9, s22, v94
	s_cbranch_scc1 .LBB0_126
	s_cmp_gt_i32 s45, 1
	s_cbranch_scc0 .LBB0_127
	s_cmp_eq_u32 s45, 2
	s_mov_b64 s[24:25], -1
	s_cbranch_scc0 .LBB0_125
	v_lshlrev_b32_e32 v10, 1, v9
	v_and_or_b32 v10, v10, s40, v113
	s_mov_b64 s[24:25], 0

; #define LAS __attribute__((address_space(3)))
; __device__ __forceinline__ int row_map(int mode, int n) {
;     if (mode == 0) return n;
;     if (mode == 1) return (n >> 7) * 256 + (n & 127);
;     if (mode == 2) return (n >> 7) * 256 + 128 + (n & 127);
;     if (n < 1024 || n >= 3072) { const int c = n & 31; return (n & ~31) + 16 * ((c >> 2) & 1) + 4 * (c >> 3) + (c & 3); }
;     const int dd = (n - 1024) & 127; return (n - dd) + ((((dd >> 4) & 3) << 5) | ((dd >> 6) << 4) | (dd & 15));
; __device__ __forceinline__ void tr_item_cu(const float* __restrict__ W, int K, int N, bf16* __restrict__ WT, const float* rowgain, int mode, LAS unsigned char* buf, int item, int wave, int lane) {
;     ...
;     for (int m = 0; m < 8; ++m) { const int row = 16 * wave + 2 * m + hr;
;         const u32x4 o = *(const LAS u32x4*)(buf + row * TCP + c * 16);
;         asm volatile("global_store_dwordx4 %0, %1, off sc1\n\ts_nop 1" :: "v"(WT + (size_t)row_map(mode, n0 + row) * K + k0 + 8 * c), "v"(o) : "memory"); }
.LBB0_137:
	v_ashrrev_i32_e32 v9, 31, v10
	v_mul_lo_u32 v12, s21, v10
	v_mul_lo_u32 v9, s20, v9
	v_mad_u64_u32 v[10:11], s[24:25], s20, v10, 0
	v_add3_u32 v11, v11, v9, v12
	v_lshl_add_u64 v[10:11], v[10:11], 1, v[6:7]
	s_waitcnt lgkmcnt(0)
	global_store_dwordx4 v[10:11], v[36:39], off
	s_nop 1
	s_cmp_lt_i32 s45, 1
	v_add_u32_e32 v9, s22, v97
	s_cbranch_scc1 .LBB0_142
	s_cmp_gt_i32 s45, 1
	s_cbranch_scc0 .LBB0_143
	s_cmp_eq_u32 s45, 2
	s_mov_b64 s[24:25], -1
	s_cbranch_scc0 .LBB0_141
	v_lshlrev_b32_e32 v10, 1, v9
	v_and_or_b32 v10, v10, s40, v114
	s_mov_b64 s[24:25], 0

; #define LAS __attribute__((address_space(3)))
; __device__ __forceinline__ int row_map(int mode, int n) {
;     if (mode == 0) return n;
;     if (mode == 1) return (n >> 7) * 256 + (n & 127);
;     if (mode == 2) return (n >> 7) * 256 + 128 + (n & 127);
;     if (n < 1024 || n >= 3072) { const int c = n & 31; return (n & ~31) + 16 * ((c >> 2) & 1) + 4 * (c >> 3) + (c & 3); }
;     const int dd = (n - 1024) & 127; return (n - dd) + ((((dd >> 4) & 3) << 5) | ((dd >> 6) << 4) | (dd & 15));
; __device__ __forceinline__ void tr_item_cu(const float* __restrict__ W, int K, int N, bf16* __restrict__ WT, const float* rowgain, int mode, LAS unsigned char* buf, int item, int wave, int lane) {
;     ...
;     for (int m = 0; m < 8; ++m) { const int row = 16 * wave + 2 * m + hr;
;         const u32x4 o = *(const LAS u32x4*)(buf + row * TCP + c * 16);
;         asm volatile("global_store_dwordx4 %0, %1, off sc1\n\ts_nop 1" :: "v"(WT + (size_t)row_map(mode, n0 + row) * K + k0 + 8 * c), "v"(o) : "memory"); }
.LBB0_153:
	v_ashrrev_i32_e32 v9, 31, v10
	v_mul_lo_u32 v12, s21, v10
	v_mul_lo_u32 v9, s20, v9
	v_mad_u64_u32 v[10:11], s[24:25], s20, v10, 0
	v_add3_u32 v11, v11, v9, v12
	v_lshl_add_u64 v[10:11], v[10:11], 1, v[6:7]
	s_waitcnt lgkmcnt(0)
	global_store_dwordx4 v[10:11], v[40:43], off
	s_nop 1
	s_cmp_lt_i32 s45, 1
	v_add_u32_e32 v9, s22, v101
	s_cbranch_scc1 .LBB0_158
	s_cmp_gt_i32 s45, 1
	s_cbranch_scc0 .LBB0_159
	s_cmp_eq_u32 s45, 2
	s_mov_b64 s[24:25], -1
	s_cbranch_scc0 .LBB0_157
	v_lshlrev_b32_e32 v10, 1, v9
	v_and_or_b32 v10, v10, s40, v115
	s_mov_b64 s[24:25], 0

; #define LAS __attribute__((address_space(3)))
; __device__ __forceinline__ int row_map(int mode, int n) {
;     if (mode == 0) return n;
;     if (mode == 1) return (n >> 7) * 256 + (n & 127);
;     if (mode == 2) return (n >> 7) * 256 + 128 + (n & 127);
;     if (n < 1024 || n >= 3072) { const int c = n & 31; return (n & ~31) + 16 * ((c >> 2) & 1) + 4 * (c >> 3) + (c & 3); }
;     const int dd = (n - 1024) & 127; return (n - dd) + ((((dd >> 4) & 3) << 5) | ((dd >> 6) << 4) | (dd & 15));
; __device__ __forceinline__ void tr_item_cu(const float* __restrict__ W, int K, int N, bf16* __restrict__ WT, const float* rowgain, int mode, LAS unsigned char* buf, int item, int wave, int lane) {
;     ...
;     for (int m = 0; m < 8; ++m) { const int row = 16 * wave + 2 * m + hr;
;         const u32x4 o = *(const LAS u32x4*)(buf + row * TCP + c * 16);
;         asm volatile("global_store_dwordx4 %0, %1, off sc1\n\ts_nop 1" :: "v"(WT + (size_t)row_map(mode, n0 + row) * K + k0 + 8 * c), "v"(o) : "memory"); }
.LBB0_169:
	v_ashrrev_i32_e32 v9, 31, v10
	v_mul_lo_u32 v12, s21, v10
	v_mul_lo_u32 v9, s20, v9
	v_mad_u64_u32 v[10:11], s[24:25], s20, v10, 0
	v_add3_u32 v11, v11, v9, v12
	v_lshl_add_u64 v[10:11], v[10:11], 1, v[6:7]
	s_waitcnt lgkmcnt(0)
	global_store_dwordx4 v[10:11], v[44:47], off
	s_nop 1
	s_cmp_lt_i32 s45, 1
	v_add_u32_e32 v8, s22, v105
	s_cbranch_scc1 .LBB0_174
	s_cmp_gt_i32 s45, 1
	s_cbranch_scc0 .LBB0_175
	s_cmp_eq_u32 s45, 2
	s_mov_b64 s[22:23], -1
	s_cbranch_scc0 .LBB0_173
	v_lshlrev_b32_e32 v9, 1, v8
	v_and_or_b32 v9, v9, s40, v116
	s_mov_b64 s[22:23], 0
